# attnB: unused bias-table fill removed from the task prologue (the extended table replaced it)
# speedup vs baseline: 1.0107x; 1.0107x over previous
; DI void task_attnB(const P& p, int layer, int task, bf16_t* sm, int dm) {
;     ...
;   const int qb = 63 - (task >> 3), bg = task & 7, b = bg >> 1, g = bg & 1, head = g * 4 + hr;
;   float* tabs = (float*)((unsigned char*)sm + 36864);
;   __syncthreads();
;   for (int i = tid; i < 4 * 129; i += NTHR) {
;     const int r = i / 129, d = i % 129;
;     tabs[r * 132 + d] = ((const float*)(p.ws + O_TABS))[(4 + g * 4 + r) * 132 + d];
;   }
;   const int q0 = qb * 64, qmin = q0 + qs * 32, qp = qmin + lr;
;   bf16_t* bq = (bf16_t*)(p.ws + O_BQ);
;   bf16x8 q[4];
;   {
;     const bf16_t* qptr = bq + (size_t)(b * S_ + qp) * 512 + head * 64 + lh * 8;
; #pragma unroll
;     for (int ks = 0; ks < 4; ++ks) q[ks] = *(const bf16x8*)(qptr + ks * 16);
;   }
;   f32x16 O[2];
; #pragma unroll
;   for (int dt = 0; dt < 2; ++dt)
; #pragma unroll
;     for (int i = 0; i < 16; ++i) O[dt][i] = 0.f;
;   float m = p.sinks[layer * 8 + head] * LOG2E, l = lh == 0 ? 1.f : 0.f;
;   const bf16_t* kg = (const bf16_t*)(p.ws + O_BK) + (size_t)b * S_ * 128 + g * 64;
;   const bf16_t* vg = (const bf16_t*)(p.ws + O_BVT) + (size_t)((b * 2 + g) * 64) * S_;
;   const int kt_lo = q0 >= 127 ? (q0 - 127) >> 6 : 0, kt_hi = qb;
;   KVRegs R;
;   kv_gload(R, kg, 128, vg, S_, kt_lo * 64);
.LBB0_895:
	v_mov_b32_e32 v246, 0xf149f2ca
	v_lshlrev_b32_e32 v244, 2, v195
	v_add_u32_e32 v244, 0x1e000, v244
	s_waitcnt vmcnt(0)
	v_cmp_gt_u32_e64 s[98:99], s101, v247
	s_nop 1
	v_cndmask_b32_e64 v196, v246, v196, s[98:99]
	v_cndmask_b32_e64 v197, v246, v197, s[98:99]
	v_cndmask_b32_e64 v198, v246, v198, s[98:99]
	v_cndmask_b32_e64 v199, v246, v199, s[98:99]
	ds_write_b32 v244, v196
	ds_write_b32 v244, v197 offset:4096
	ds_write_b32 v244, v198 offset:8192
	ds_write_b32 v244, v199 offset:12288
	s_add_i32 s1, s34, 0xfffffbf0
	s_lshr_b32 s0, s1, 3
	v_bfe_u32 v2, v0, 6, 2
	v_and_b32_e32 v1, 31, v0
	v_bfe_u32 v91, v0, 5, 1
	s_xor_b32 s25, s0, 63
	v_ashrrev_i32_e32 v0, 3, v0
	s_lshl_b32 s0, s25, 6
	v_and_b32_e32 v3, 0xffffffe0, v0
	v_add_u32_e32 v0, s0, v3
	s_bfe_u32 s2, s34, 0x20001
	v_or_b32_e32 v92, v0, v1
	v_lshl_add_u32 v4, s2, 12, v92
	v_ashrrev_i32_e32 v5, 31, v4
	v_or_b32_e32 v6, s7, v2
	v_lshlrev_b64 v[4:5], 10, v[4:5]
	v_lshl_add_u64 v[4:5], s[52:53], 0, v[4:5]
	v_lshlrev_b32_e32 v192, 7, v6
	v_lshl_add_u64 v[56:57], v[4:5], 0, v[192:193]
	v_lshlrev_b32_e32 v192, 4, v91
	v_lshl_add_u64 v[4:5], v[56:57], 0, v[192:193]
	v_readlane_b32 s3, v255, 15
	v_readlane_b32 s36, v253, 6
	global_load_dwordx4 v[32:35], v[4:5], off
	global_load_dwordx4 v[36:39], v[4:5], off offset:32
	global_load_dwordx4 v[40:43], v[4:5], off offset:64
	global_load_dwordx4 v[44:47], v[4:5], off offset:96
	v_or_b32_e32 v192, s3, v6
	v_readlane_b32 s46, v253, 16
	v_readlane_b32 s47, v253, 17
	s_add_i32 s3, s0, 0xffffff81
	s_ashr_i32 s3, s3, 6
	v_lshl_add_u64 v[4:5], v[192:193], 2, s[46:47]
	global_load_dword v4, v[4:5], off
	s_cmp_gt_u32 s25, 1
	v_cmp_eq_u32_e32 vcc, 0, v91
	s_cselect_b32 s30, s3, 0
	v_mov_b32_e32 v59, 0
	v_cndmask_b32_e64 v98, 0, 1.0, vcc
	v_mov_b32_e32 v5, v195
	s_cmp_le_i32 s30, s25
	v_readlane_b32 s37, v253, 7
	v_readlane_b32 s38, v253, 8
	v_readlane_b32 s39, v253, 9
	v_readlane_b32 s40, v253, 10
	v_readlane_b32 s41, v253, 11
	v_readlane_b32 s42, v253, 12
	v_readlane_b32 s43, v253, 13
	v_readlane_b32 s44, v253, 14
	v_readlane_b32 s45, v253, 15
	v_readlane_b32 s48, v253, 18
	v_readlane_b32 s49, v253, 19
	v_readlane_b32 s50, v253, 20
	v_readlane_b32 s51, v253, 21
	s_cbranch_scc0 .LBB0_1075
	s_lshl_b32 s2, s2, 20
	v_readlane_b32 s4, v253, 48
	v_readlane_b32 s5, v253, 49
	s_add_u32 s2, s4, s2
	s_addc_u32 s3, s5, 0
	s_lshl_b32 s4, s6, 7
	s_add_u32 s2, s2, s4
	s_addc_u32 s3, s3, 0
	s_lshl_b32 s1, s1, 19
	s_and_b32 s1, s1, 0x380000
	v_readlane_b32 s4, v253, 46
	v_readlane_b32 s5, v253, 47
	s_add_u32 s4, s4, s1
	v_ashrrev_i32_e32 v6, 3, v5
	s_addc_u32 s5, s5, 0
	v_ashrrev_i32_e32 v7, 31, v6
	s_lshl_b32 s6, s30, 6
	v_lshlrev_b64 v[8:9], 13, v[6:7]
	v_add_u32_e32 v6, s6, v6
	v_lshl_add_u64 v[8:9], s[4:5], 0, v[8:9]
	s_ashr_i32 s7, s6, 31
	v_lshlrev_b32_e32 v5, 4, v5
	v_ashrrev_i32_e32 v7, 31, v6
	v_lshl_add_u64 v[8:9], s[6:7], 1, v[8:9]
	v_and_b32_e32 v192, 0x70, v5
	v_lshlrev_b64 v[6:7], 8, v[6:7]
	v_lshl_add_u64 v[8:9], v[8:9], 0, v[192:193]
	v_lshl_add_u64 v[6:7], s[2:3], 0, v[6:7]
	v_lshl_add_u64 v[6:7], v[6:7], 0, v[192:193]
	global_load_dwordx4 v[52:55], v[8:9], off
	global_load_dwordx4 v[48:51], v[6:7], off
	v_add_u32_e32 v93, 0xffffff42, v0
	v_or_b32_e32 v94, 31, v0
	v_add_u32_e32 v0, v0, v1
	s_sub_i32 s0, s0, 59
	v_subrev_u32_e32 v0, s6, v0
	s_waitcnt vmcnt(2)
	v_mul_f32_e32 v90, 0x3fb8aa3b, v4
	v_mul_u32_u24_e32 v4, 0x210, v2
	v_mad_u32_u24 v95, v2, s92, 0
	v_add3_u32 v2, s0, v3, v1
	v_lshlrev_b32_e32 v0, 2, v0
	v_readlane_b32 s0, v255, 4
	v_mov_b32_e32 v86, 0
	v_subrev_u32_e32 v96, s6, v2
	v_add3_u32 v97, v4, v0, s0
	v_mov_b32_e32 v87, v86
	v_mov_b32_e32 v88, v86
	v_mov_b32_e32 v89, v86
	v_mov_b32_e32 v84, v86
	v_mov_b32_e32 v85, v86
	v_mov_b32_e32 v82, v86
	v_mov_b32_e32 v83, v86
	v_mov_b32_e32 v80, v86
	v_mov_b32_e32 v81, v86
	v_mov_b32_e32 v76, v86
	v_mov_b32_e32 v77, v86
	v_mov_b32_e32 v72, v86
	v_mov_b32_e32 v73, v86
	v_mov_b32_e32 v68, v86
	v_mov_b32_e32 v69, v86
	v_mov_b32_e32 v78, v86
	v_mov_b32_e32 v79, v86
	v_mov_b32_e32 v74, v86
	v_mov_b32_e32 v75, v86
	v_mov_b32_e32 v70, v86
	v_mov_b32_e32 v71, v86
	v_mov_b32_e32 v66, v86
	v_mov_b32_e32 v67, v86
	v_mov_b32_e32 v64, v86
	v_mov_b32_e32 v65, v86
	v_mov_b32_e32 v62, v86
	v_mov_b32_e32 v63, v86
	v_mov_b32_e32 v60, v86
	v_mov_b32_e32 v61, v86
	v_mov_b32_e32 v58, v86
	v_mov_b32_e32 v59, v86
	s_branch .LBB0_900
